# P3 combine: last loop iteration's y stores write-through (barrier 4 flushes less)
# baseline (speedup 1.0000x reference)
.LBB0_437:
	v_lshrrev_b64 v[8:9], 16, v[14:15]
	v_bfe_u32 v16, v14, 4, 12
	v_alignbit_b32 v5, v15, v14, 16
	v_lshl_add_u64 v[6:7], v[14:15], 0, s[46:47]
	v_lshlrev_b64 v[8:9], 12, v[8:9]
	v_lshrrev_b32_e32 v17, 9, v14
	v_add_u32_e32 v18, s20, v14
	v_lshl_add_u64 v[10:11], s[22:23], 0, v[14:15]
	v_add_u32_e32 v19, s0, v14
	v_lshl_add_u64 v[12:13], s[50:51], 0, v[14:15]
	v_add_u32_e32 v14, s1, v14
	v_lshlrev_b32_e32 v15, 9, v5
	v_alignbit_b32 v5, v7, v6, 16
	v_or_b32_e32 v8, v8, v16
	v_lshrrev_b32_e32 v20, 4, v18
	v_bfe_u32 v18, v18, 4, 12
	v_lshrrev_b32_e32 v26, 4, v19
	v_bfe_u32 v27, v19, 4, 12
	v_lshrrev_b32_e32 v61, 9, v10
	v_lshrrev_b32_e32 v28, 4, v14
	v_bfe_u32 v29, v14, 4, 12
	v_and_or_b32 v16, v15, s34, v16
	v_ashrrev_i64 v[14:15], 20, v[4:5]
	v_lshlrev_b32_e32 v19, 9, v5
	v_alignbit_b32 v5, v11, v10, 16
	v_lshlrev_b64 v[10:11], 8, v[8:9]
	v_lshl_add_u64 v[8:9], v[8:9], 2, s[52:53]
	v_lshrrev_b32_e32 v62, 9, v12
	v_lshlrev_b32_e32 v22, 11, v16
	v_or_b32_e32 v14, v14, v18
	v_bfi_b32 v16, s36, v19, v20
	v_ashrrev_i64 v[18:19], 20, v[4:5]
	v_lshlrev_b32_e32 v30, 9, v5
	v_alignbit_b32 v5, v13, v12, 16
	v_add_co_u32_e32 v12, vcc, s3, v8
	v_and_b32_e32 v1, 0x78, v2
	s_nop 0
	v_addc_co_u32_e32 v13, vcc, 0, v9, vcc
	v_and_b32_e32 v17, 0x380, v17
	v_add_co_u32_e32 v20, vcc, s21, v8
	s_add_u32 s4, s46, s46
	s_nop 0
	v_addc_co_u32_e32 v21, vcc, 0, v9, vcc
	v_or3_b32 v31, v17, v22, v1
	v_lshl_add_u64 v[22:23], v[14:15], 2, s[52:53]
	s_addc_u32 s5, s47, s47
	v_add_co_u32_e32 v42, vcc, s3, v22
	v_lshlrev_b32_e32 v60, 1, v1
	s_add_u32 s4, s4, s46
	v_addc_co_u32_e32 v43, vcc, 0, v23, vcc
	s_addc_u32 s5, s5, s47
	v_or_b32_e32 v10, v10, v60
	v_lshlrev_b64 v[24:25], 8, v[14:15]
	v_or_b32_e32 v18, v18, v27
	v_ashrrev_i64 v[36:37], 20, v[4:5]
	v_add_co_u32_e32 v44, vcc, s21, v22
	v_lshrrev_b32_e32 v48, 9, v6
	v_ashrrev_i32_e32 v17, 31, v16
	v_bfi_b32 v30, s36, v30, v26
	v_lshlrev_b32_e32 v26, 9, v5
	v_lshl_add_u64 v[14:15], s[4:5], 0, v[6:7]
	v_lshl_add_u64 v[6:7], s[24:25], 0, v[10:11]
	v_lshl_add_u64 v[38:39], s[12:13], 0, v[10:11]
	v_lshl_add_u64 v[10:11], s[42:43], 0, v[10:11]
	v_or_b32_e32 v24, v24, v60
	v_addc_co_u32_e32 v45, vcc, 0, v23, vcc
	v_lshlrev_b64 v[46:47], 8, v[18:19]
	v_lshl_add_u64 v[18:19], v[18:19], 2, s[52:53]
	v_or_b32_e32 v36, v36, v29
	v_lshlrev_b32_e32 v5, 1, v31
	global_load_dword v63, v[22:23], off
	v_lshlrev_b64 v[16:17], 11, v[16:17]
	v_bfi_b32 v52, s36, v26, v28
	v_cmp_lt_u64_e32 vcc, s[56:57], v[14:15]
	global_load_dword v64, v[8:9], off
	global_load_dword v65, v[12:13], off
	global_load_dword v68, v[20:21], off
	s_nop 0
	global_load_dwordx4 v[20:23], v[10:11], off
	global_load_dwordx4 v[26:29], v5, s[48:49]
	global_load_dwordx4 v[32:35], v[6:7], off
	s_nop 0
	global_load_dwordx4 v[38:41], v[38:39], off
	v_lshl_add_u64 v[6:7], s[24:25], 0, v[24:25]
	v_lshl_add_u64 v[8:9], s[12:13], 0, v[24:25]
	v_lshl_add_u64 v[10:11], s[42:43], 0, v[24:25]
	v_or_b32_e32 v46, v46, v60
	v_add_co_u32_e64 v12, s[4:5], s3, v18
	v_lshlrev_b64 v[54:55], 8, v[36:37]
	v_lshl_add_u64 v[36:37], v[36:37], 2, s[52:53]
	v_ashrrev_i32_e32 v31, 31, v30
	global_load_dword v69, v[42:43], off
	global_load_dword v82, v[44:45], off
	v_and_or_b32 v16, v48, s35, v16
	v_addc_co_u32_e64 v13, s[4:5], 0, v19, s[4:5]
	s_or_b64 s[54:55], vcc, s[54:55]
	global_load_dwordx4 v[42:45], v[6:7], off
	global_load_dwordx4 v[48:51], v[8:9], off
	global_load_dwordx4 v[56:59], v[10:11], off
	v_lshl_add_u64 v[6:7], s[24:25], 0, v[46:47]
	v_lshl_add_u64 v[8:9], s[12:13], 0, v[46:47]
	v_lshl_add_u64 v[10:11], s[42:43], 0, v[46:47]
	v_add_co_u32_e32 v46, vcc, s3, v36
	v_add_co_u32_e64 v24, s[4:5], s21, v18
	v_lshlrev_b64 v[30:31], 11, v[30:31]
	v_ashrrev_i32_e32 v53, 31, v52
	v_or_b32_e32 v16, v16, v1
	v_addc_co_u32_e32 v47, vcc, 0, v37, vcc
	v_addc_co_u32_e64 v25, s[4:5], 0, v19, s[4:5]
	v_and_or_b32 v30, v61, s35, v30
	v_or_b32_e32 v54, v54, v60
	global_load_dword v60, v[36:37], off
	v_add_co_u32_e32 v36, vcc, s21, v36
	v_lshlrev_b64 v[52:53], 11, v[52:53]
	v_lshlrev_b64 v[16:17], 1, v[16:17]
	global_load_dwordx4 v[120:123], v[6:7], off
	global_load_dwordx4 v[124:127], v[8:9], off
	global_load_dwordx4 v[128:131], v[10:11], off
	global_load_dword v83, v[18:19], off
	global_load_dword v88, v[12:13], off
	global_load_dword v89, v[24:25], off
	v_addc_co_u32_e32 v37, vcc, 0, v37, vcc
	v_or_b32_e32 v30, v30, v1
	v_lshl_add_u64 v[6:7], s[24:25], 0, v[54:55]
	v_lshl_add_u64 v[8:9], s[12:13], 0, v[54:55]
	v_lshl_add_u64 v[10:11], s[42:43], 0, v[54:55]
	global_load_dword v46, v[46:47], off
	s_nop 0
	global_load_dword v54, v[36:37], off
	v_and_or_b32 v24, v62, s35, v52
	v_lshl_add_u64 v[12:13], s[48:49], 0, v[16:17]
	v_lshlrev_b64 v[18:19], 1, v[30:31]
	global_load_dwordx4 v[142:145], v[8:9], off
	global_load_dwordx4 v[146:149], v[10:11], off
	v_or_b32_e32 v52, v24, v1
	global_load_dwordx4 v[150:153], v[12:13], off
	v_lshl_add_u64 v[10:11], s[18:19], 0, v[16:17]
	v_lshl_add_u64 v[12:13], s[48:49], 0, v[18:19]
	v_lshlrev_b64 v[16:17], 1, v[52:53]
	global_load_dwordx4 v[154:157], v[12:13], off
	global_load_dwordx4 v[158:161], v[6:7], off
	v_lshl_add_u64 v[12:13], s[48:49], 0, v[16:17]
	global_load_dwordx4 v[162:165], v[12:13], off
	v_lshl_add_u64 v[8:9], s[18:19], 0, v[18:19]
	v_lshl_add_u64 v[6:7], s[18:19], 0, v[16:17]
	v_lshl_add_u64 v[2:3], v[2:3], 0, s[44:45]
	s_waitcnt vmcnt(24)
	v_max3_f32 v1, v64, v65, v68
	s_waitcnt vmcnt(23)
	v_lshlrev_b32_e32 v31, 16, v21
	v_and_b32_e32 v25, 0xffff0000, v21
	v_lshlrev_b32_e32 v21, 16, v22
	v_and_b32_e32 v19, 0xffff0000, v22
	v_lshlrev_b32_e32 v67, 16, v20
	s_waitcnt vmcnt(22)
	v_lshlrev_b32_e32 v66, 16, v26
	v_and_b32_e32 v37, 0xffff0000, v20
	v_and_b32_e32 v36, 0xffff0000, v26
	v_lshlrev_b32_e32 v30, 16, v27
	v_and_b32_e32 v24, 0xffff0000, v27
	v_lshlrev_b32_e32 v20, 16, v28
	v_and_b32_e32 v18, 0xffff0000, v28
	v_lshlrev_b32_e32 v16, 16, v29
	s_waitcnt vmcnt(18)
	v_max3_f32 v22, v63, v69, v82
	v_sub_f32_e32 v26, v64, v1
	v_sub_f32_e32 v28, v65, v1
	v_sub_f32_e32 v61, v63, v22
	v_sub_f32_e32 v62, v69, v22
	v_sub_f32_e32 v22, v82, v22
	v_lshlrev_b32_e32 v71, 16, v38
	v_lshlrev_b32_e32 v70, 16, v32
	v_and_b32_e32 v73, 0xffff0000, v38
	v_and_b32_e32 v72, 0xffff0000, v32
	v_lshlrev_b32_e32 v79, 16, v40
	v_lshlrev_b32_e32 v78, 16, v34
	v_and_b32_e32 v81, 0xffff0000, v40
	v_and_b32_e32 v80, 0xffff0000, v34
	v_lshlrev_b32_e32 v85, 16, v41
	v_lshlrev_b32_e32 v84, 16, v35
	v_and_b32_e32 v87, 0xffff0000, v41
	v_and_b32_e32 v86, 0xffff0000, v35
	v_sub_f32_e32 v1, v68, v1
	v_mul_f32_e32 v32, 0xbfb8aa3b, v66
	v_mul_f32_e32 v34, 0xbfb8aa3b, v36
	v_mul_f32_e32 v35, 0xbfb8aa3b, v30
	v_mul_f32_e32 v38, 0xbfb8aa3b, v24
	v_mul_f32_e32 v40, 0xbfb8aa3b, v20
	v_mul_f32_e32 v41, 0xbfb8aa3b, v18
	v_mul_f32_e32 v52, 0xbfb8aa3b, v16
	v_exp_f32_e32 v166, v26
	v_exp_f32_e32 v167, v28
	v_exp_f32_e32 v168, v61
	v_exp_f32_e32 v169, v62
	v_exp_f32_e32 v172, v22
	s_waitcnt vmcnt(8)
	v_max3_f32 v22, v83, v88, v89
	v_lshlrev_b32_e32 v74, 16, v33
	v_and_b32_e32 v76, 0xffff0000, v33
	v_and_b32_e32 v12, 0xffff0000, v29
	v_lshlrev_b32_e32 v33, 16, v58
	v_and_b32_e32 v29, 0xffff0000, v58
	v_lshlrev_b32_e32 v101, 16, v50
	v_lshlrev_b32_e32 v100, 16, v44
	v_and_b32_e32 v103, 0xffff0000, v50
	v_and_b32_e32 v102, 0xffff0000, v44
	v_exp_f32_e32 v1, v1
	v_exp_f32_e32 v44, v32
	v_exp_f32_e32 v50, v34
	v_exp_f32_e32 v58, v35
	v_exp_f32_e32 v68, v38
	v_exp_f32_e32 v82, v40
	v_exp_f32_e32 v170, v41
	v_exp_f32_e32 v52, v52
	s_waitcnt vmcnt(6)
	v_max3_f32 v26, v60, v46, v54
	v_sub_f32_e32 v34, v83, v22
	v_sub_f32_e32 v40, v88, v22
	v_lshlrev_b32_e32 v91, 16, v56
	v_and_b32_e32 v55, 0xffff0000, v56
	v_lshlrev_b32_e32 v93, 16, v48
	v_lshlrev_b32_e32 v92, 16, v42
	v_and_b32_e32 v95, 0xffff0000, v48
	v_and_b32_e32 v94, 0xffff0000, v42
	v_lshlrev_b32_e32 v41, 16, v131
	v_and_b32_e32 v35, 0xffff0000, v131
	v_sub_f32_e32 v42, v89, v22
	v_sub_f32_e32 v48, v60, v26
	v_sub_f32_e32 v56, v46, v26
	s_waitcnt vmcnt(5)
	v_lshlrev_b32_e32 v139, 16, v143
	v_and_b32_e32 v131, 0xffff0000, v143
	v_lshlrev_b32_e32 v137, 16, v144
	v_and_b32_e32 v133, 0xffff0000, v144
	v_lshlrev_b32_e32 v135, 16, v145
	v_and_b32_e32 v143, 0xffff0000, v145
	s_waitcnt vmcnt(3)
	v_lshlrev_b32_e32 v90, 16, v150
	v_lshlrev_b32_e32 v46, 16, v151
	v_exp_f32_e32 v144, v34
	v_exp_f32_e32 v145, v40
	v_mul_f32_e32 v53, 0xbfb8aa3b, v12
	v_lshlrev_b32_e32 v111, 16, v124
	v_and_b32_e32 v113, 0xffff0000, v124
	v_lshlrev_b32_e32 v114, 16, v121
	v_and_b32_e32 v116, 0xffff0000, v121
	v_lshlrev_b32_e32 v119, 16, v126
	v_and_b32_e32 v121, 0xffff0000, v126
	v_lshlrev_b32_e32 v124, 16, v123
	v_and_b32_e32 v126, 0xffff0000, v123
	v_sub_f32_e32 v60, v54, v26
	v_lshlrev_b32_e32 v123, 16, v146
	v_and_b32_e32 v83, 0xffff0000, v146
	v_lshlrev_b32_e32 v69, 16, v147
	v_and_b32_e32 v63, 0xffff0000, v147
	v_and_b32_e32 v38, 0xffff0000, v151
	v_lshlrev_b32_e32 v32, 16, v152
	v_exp_f32_e32 v151, v42
	v_exp_f32_e32 v146, v48
	v_exp_f32_e32 v147, v56
	v_mul_f32_e32 v62, 0xbfb8aa3b, v90
	v_mul_f32_e32 v89, 0xbfb8aa3b, v46
	v_lshlrev_b32_e32 v17, 16, v23
	v_and_b32_e32 v13, 0xffff0000, v23
	v_lshlrev_b32_e32 v27, 16, v59
	v_and_b32_e32 v23, 0xffff0000, v59
	v_exp_f32_e32 v171, v53
	v_lshlrev_b32_e32 v110, 16, v120
	v_and_b32_e32 v112, 0xffff0000, v120
	v_lshlrev_b32_e32 v118, 16, v122
	v_and_b32_e32 v120, 0xffff0000, v122
	v_lshlrev_b32_e32 v59, 16, v148
	v_and_b32_e32 v53, 0xffff0000, v148
	v_and_b32_e32 v54, 0xffff0000, v150
	v_lshlrev_b32_e32 v26, 16, v153
	v_and_b32_e32 v22, 0xffff0000, v153
	v_exp_f32_e32 v153, v60
	v_mul_f32_e32 v122, 0xbfb8aa3b, v38
	v_mul_f32_e32 v148, 0xbfb8aa3b, v32
	s_waitcnt vmcnt(2)
	v_lshlrev_b32_e32 v108, 16, v154
	v_and_b32_e32 v64, 0xffff0000, v154
	v_lshlrev_b32_e32 v60, 16, v155
	v_and_b32_e32 v56, 0xffff0000, v155
	v_lshlrev_b32_e32 v48, 16, v156
	v_and_b32_e32 v42, 0xffff0000, v156
	v_lshlrev_b32_e32 v40, 16, v157
	v_and_b32_e32 v34, 0xffff0000, v157
	v_add_f32_e32 v154, v166, v167
	v_add_f32_e32 v156, v168, v169
	v_exp_f32_e32 v173, v62
	v_exp_f32_e32 v89, v89
	v_lshlrev_b32_e32 v75, 16, v39
	v_and_b32_e32 v77, 0xffff0000, v39
	v_lshlrev_b32_e32 v47, 16, v57
	v_and_b32_e32 v39, 0xffff0000, v57
	v_lshlrev_b32_e32 v97, 16, v49
	v_lshlrev_b32_e32 v96, 16, v43
	v_and_b32_e32 v99, 0xffff0000, v49
	v_and_b32_e32 v98, 0xffff0000, v43
	v_lshlrev_b32_e32 v109, 16, v128
	v_and_b32_e32 v65, 0xffff0000, v128
	v_lshlrev_b32_e32 v61, 16, v129
	v_and_b32_e32 v57, 0xffff0000, v129
	v_lshlrev_b32_e32 v49, 16, v130
	v_and_b32_e32 v43, 0xffff0000, v130
	v_lshlrev_b32_e32 v141, 16, v142
	v_and_b32_e32 v129, 0xffff0000, v142
	v_mul_f32_e32 v88, 0xbfb8aa3b, v54
	s_waitcnt vmcnt(1)
	v_lshlrev_b32_e32 v140, 16, v158
	v_and_b32_e32 v128, 0xffff0000, v158
	v_lshlrev_b32_e32 v138, 16, v159
	v_and_b32_e32 v130, 0xffff0000, v159
	v_lshlrev_b32_e32 v136, 16, v160
	v_and_b32_e32 v132, 0xffff0000, v160
	v_lshlrev_b32_e32 v134, 16, v161
	v_and_b32_e32 v142, 0xffff0000, v161
	v_add_f32_e32 v155, 1.0, v44
	v_add_f32_e32 v157, 1.0, v50
	v_add_f32_e32 v158, 1.0, v58
	v_add_f32_e32 v159, 1.0, v68
	v_add_f32_e32 v160, 1.0, v82
	v_add_f32_e32 v161, 1.0, v170
	v_add_f32_e32 v170, 1.0, v52
	v_exp_f32_e32 v175, v122
	v_exp_f32_e32 v148, v148
	v_mul_f32_e32 v176, 0xbfb8aa3b, v108
	v_mul_f32_e32 v177, 0xbfb8aa3b, v64
	v_mul_f32_e32 v178, 0xbfb8aa3b, v60
	v_mul_f32_e32 v179, 0xbfb8aa3b, v56
	v_mul_f32_e32 v180, 0xbfb8aa3b, v48
	v_mul_f32_e32 v181, 0xbfb8aa3b, v42
	v_mul_f32_e32 v182, 0xbfb8aa3b, v40
	v_mul_f32_e32 v183, 0xbfb8aa3b, v34
	s_waitcnt vmcnt(0)
	v_lshlrev_b32_e32 v122, 16, v162
	v_and_b32_e32 v82, 0xffff0000, v162
	v_lshlrev_b32_e32 v68, 16, v163
	v_and_b32_e32 v62, 0xffff0000, v163
	v_lshlrev_b32_e32 v58, 16, v164
	v_and_b32_e32 v52, 0xffff0000, v164
	v_lshlrev_b32_e32 v50, 16, v165
	v_and_b32_e32 v44, 0xffff0000, v165
	v_add_f32_e32 v154, v1, v154
	v_add_f32_e32 v156, v172, v156
	v_and_b32_e32 v28, 0xffff0000, v152
	v_mul_f32_e32 v150, 0xbfb8aa3b, v26
	v_mul_f32_e32 v152, 0xbfb8aa3b, v22
	v_exp_f32_e32 v174, v88
	v_rcp_f32_e32 v88, v155
	v_exp_f32_e32 v155, v176
	v_exp_f32_e32 v162, v177
	v_exp_f32_e32 v163, v178
	v_exp_f32_e32 v164, v179
	v_exp_f32_e32 v165, v180
	v_exp_f32_e32 v176, v181
	v_exp_f32_e32 v177, v182
	v_exp_f32_e32 v178, v183
	v_mul_f32_e32 v179, 0xbfb8aa3b, v122
	v_mul_f32_e32 v180, 0xbfb8aa3b, v82
	v_mul_f32_e32 v181, 0xbfb8aa3b, v68
	v_mul_f32_e32 v182, 0xbfb8aa3b, v62
	v_mul_f32_e32 v183, 0xbfb8aa3b, v58
	v_mul_f32_e32 v184, 0xbfb8aa3b, v52
	v_mul_f32_e32 v185, 0xbfb8aa3b, v50
	v_mul_f32_e32 v186, 0xbfb8aa3b, v44
	v_div_scale_f32 v187, s[4:5], v154, v154, 1.0
	v_div_scale_f32 v189, s[4:5], v156, v156, 1.0
	v_add_f32_e32 v191, v144, v145
	v_exp_f32_e32 v150, v150
	v_exp_f32_e32 v152, v152
	v_add_f32_e32 v192, v146, v147
	v_exp_f32_e32 v179, v179
	v_exp_f32_e32 v180, v180
	v_exp_f32_e32 v181, v181
	v_exp_f32_e32 v182, v182
	v_exp_f32_e32 v183, v183
	v_exp_f32_e32 v184, v184
	v_exp_f32_e32 v185, v185
	v_exp_f32_e32 v186, v186
	v_rcp_f32_e32 v193, v187
	v_rcp_f32_e32 v194, v189
	v_add_f32_e32 v191, v151, v191
	v_add_f32_e32 v192, v153, v192
	v_add_f32_e32 v173, 1.0, v173
	v_add_f32_e32 v195, 1.0, v89
	v_div_scale_f32 v89, s[6:7], v191, v191, 1.0
	v_lshlrev_b32_e32 v105, 16, v51
	v_lshlrev_b32_e32 v104, 16, v45
	v_and_b32_e32 v107, 0xffff0000, v51
	v_and_b32_e32 v106, 0xffff0000, v45
	v_lshlrev_b32_e32 v51, 16, v149
	v_and_b32_e32 v45, 0xffff0000, v149
	v_mul_f32_e32 v149, 0xbfb8aa3b, v28
	v_add_f32_e32 v196, 1.0, v148
	v_div_scale_f32 v200, s[8:9], v192, v192, 1.0
	v_rcp_f32_e32 v148, v173
	v_rcp_f32_e32 v173, v89
	v_exp_f32_e32 v149, v149
	v_rcp_f32_e32 v202, v200
	v_add_f32_e32 v198, 1.0, v150
	v_add_f32_e32 v199, 1.0, v152
	v_add_f32_e32 v150, 1.0, v155
	v_add_f32_e32 v152, 1.0, v179
	v_add_f32_e32 v179, 1.0, v180
	v_add_f32_e32 v180, 1.0, v181
	v_add_f32_e32 v181, 1.0, v182
	v_add_f32_e32 v182, 1.0, v183
	v_add_f32_e32 v183, 1.0, v184
	v_add_f32_e32 v184, 1.0, v185
	v_add_f32_e32 v185, 1.0, v186
	v_fma_f32 v155, -v187, v193, 1.0
	v_fma_f32 v186, -v189, v194, 1.0
	v_div_scale_f32 v188, vcc, 1.0, v154, 1.0
	v_div_scale_f32 v190, s[4:5], 1.0, v156, 1.0
	v_fmac_f32_e32 v193, v155, v193
	v_fmac_f32_e32 v194, v186, v194
	v_mul_f32_e32 v155, v188, v193
	v_mul_f32_e32 v186, v190, v194
	v_fma_f32 v203, -v89, v173, 1.0
	v_add_f32_e32 v197, 1.0, v149
	v_div_scale_f32 v149, s[6:7], 1.0, v191, 1.0
	v_fma_f32 v204, -v200, v202, 1.0
	v_fma_f32 v205, -v187, v155, v188
	v_fma_f32 v206, -v189, v186, v190
	v_fmac_f32_e32 v173, v203, v173
	v_div_scale_f32 v201, s[8:9], 1.0, v192, 1.0
	v_fmac_f32_e32 v202, v204, v202
	v_fmac_f32_e32 v155, v205, v193
	v_fmac_f32_e32 v186, v206, v194
	v_mul_f32_e32 v203, v149, v173
	v_mul_f32_e32 v204, v201, v202
	v_fma_f32 v187, -v187, v155, v188
	v_fma_f32 v188, -v189, v186, v190
	v_fma_f32 v189, -v89, v203, v149
	v_fma_f32 v190, -v200, v204, v201
	v_div_fmas_f32 v155, v187, v193, v155
	v_fmac_f32_e32 v203, v189, v173
	s_mov_b64 vcc, s[4:5]
	v_rcp_f32_e32 v150, v150
	v_fmac_f32_e32 v204, v190, v202
	v_div_fixup_f32 v154, v155, v154, 1.0
	v_div_fmas_f32 v186, v188, v194, v186
	v_fma_f32 v149, -v89, v203, v149
	s_mov_b64 vcc, s[6:7]
	v_rcp_f32_e32 v152, v152
	v_fma_f32 v187, -v200, v204, v201
	v_mul_f32_e32 v89, v1, v154
	v_pk_mul_f32 v[154:155], v[166:167], v[154:155] op_sel_hi:[1,0]
	v_div_fixup_f32 v156, v186, v156, 1.0
	v_div_fmas_f32 v1, v149, v173, v203
	s_mov_b64 vcc, s[8:9]
	v_add_f32_e32 v174, 1.0, v174
	v_pk_mul_f32 v[66:67], v[88:89], v[66:67]
	v_rcp_f32_e32 v88, v157
	v_pk_mul_f32 v[70:71], v[154:155], v[70:71]
	v_pk_mul_f32 v[72:73], v[154:155], v[72:73]
	v_pk_mul_f32 v[74:75], v[154:155], v[74:75]
	v_pk_mul_f32 v[76:77], v[154:155], v[76:77]
	v_pk_mul_f32 v[78:79], v[154:155], v[78:79]
	v_pk_mul_f32 v[80:81], v[154:155], v[80:81]
	v_pk_mul_f32 v[84:85], v[154:155], v[84:85]
	v_pk_mul_f32 v[86:87], v[154:155], v[86:87]
	v_mul_f32_e32 v149, v172, v156
	v_pk_mul_f32 v[154:155], v[168:169], v[156:157] op_sel_hi:[1,0]
	v_div_fixup_f32 v156, v1, v191, 1.0
	v_div_fmas_f32 v1, v187, v202, v204
	v_add_f32_e32 v162, 1.0, v162
	v_add_f32_e32 v157, v70, v71
	v_add_f32_e32 v166, v72, v73
	v_add_f32_e32 v167, v74, v75
	v_pk_mul_f32 v[70:71], v[148:149], v[90:91]
	v_rcp_f32_e32 v148, v174
	v_pk_mul_f32 v[72:73], v[154:155], v[92:93]
	v_pk_mul_f32 v[74:75], v[154:155], v[94:95]
	v_mul_f32_e32 v151, v151, v156
	v_div_fixup_f32 v94, v1, v192, 1.0
	v_add_f32_e32 v1, v67, v157
	v_add_f32_e32 v67, v72, v73
	v_pk_mul_f32 v[72:73], v[150:151], v[108:109]
	v_rcp_f32_e32 v150, v162
	v_mul_f32_e32 v153, v153, v94
	v_mul_f32_e32 v1, v66, v1
	v_add_f32_e32 v71, v71, v67
	v_pk_mul_f32 v[66:67], v[152:153], v[122:123]
	v_rcp_f32_e32 v152, v179
	v_pk_mul_f32 v[36:37], v[88:89], v[36:37]
	v_rcp_f32_e32 v88, v158
	v_add_f32_e32 v163, 1.0, v163
	v_add_f32_e32 v168, v76, v77
	v_pk_mul_f32 v[76:77], v[154:155], v[96:97]
	v_pk_mul_f32 v[92:93], v[144:145], v[156:157] op_sel_hi:[1,0]
	v_add_f32_e32 v96, v74, v75
	v_add_f32_e32 v37, v37, v166
	v_pk_mul_f32 v[54:55], v[148:149], v[54:55]
	v_rcp_f32_e32 v148, v195
	v_add_f32_e32 v97, v76, v77
	v_pk_mul_f32 v[74:75], v[92:93], v[110:111]
	v_pk_mul_f32 v[76:77], v[92:93], v[112:113]
	v_pk_mul_f32 v[94:95], v[146:147], v[94:95] op_sel_hi:[1,0]
	v_mul_f32_e32 v36, v36, v37
	v_add_f32_e32 v37, v55, v96
	v_pk_mul_f32 v[64:65], v[150:151], v[64:65]
	v_rcp_f32_e32 v150, v163
	v_add_f32_e32 v173, v84, v85
	v_add_f32_e32 v186, v86, v87
	v_pk_mul_f32 v[84:85], v[154:155], v[102:103]
	v_pk_mul_f32 v[86:87], v[154:155], v[104:105]
	v_add_f32_e32 v103, v74, v75
	v_add_f32_e32 v104, v76, v77
	v_pk_mul_f32 v[74:75], v[94:95], v[140:141]
	v_pk_mul_f32 v[76:77], v[94:95], v[128:129]
	v_cvt_pk_bf16_f32 v36, v1, v36
	v_mul_f32_e32 v1, v54, v37
	v_pk_mul_f32 v[54:55], v[152:153], v[82:83]
	v_rcp_f32_e32 v152, v180
	v_add_f32_e32 v175, 1.0, v175
	v_mul_f32_e32 v70, v70, v71
	v_add_f32_e32 v71, v73, v103
	v_add_f32_e32 v73, v74, v75
	v_add_f32_e32 v74, v76, v77
	v_add_f32_e32 v37, v65, v104
	v_pk_mul_f32 v[30:31], v[88:89], v[30:31]
	v_rcp_f32_e32 v88, v159
	v_lshlrev_b32_e32 v115, 16, v125
	v_add_f32_e32 v164, 1.0, v164
	v_add_f32_e32 v169, v78, v79
	v_pk_mul_f32 v[78:79], v[154:155], v[98:99]
	v_mul_f32_e32 v64, v64, v37
	v_add_f32_e32 v37, v55, v74
	v_add_f32_e32 v31, v31, v167
	v_pk_mul_f32 v[46:47], v[148:149], v[46:47]
	v_rcp_f32_e32 v148, v175
	v_add_f32_e32 v98, v78, v79
	v_pk_mul_f32 v[78:79], v[92:93], v[114:115]
	v_mul_f32_e32 v54, v54, v37
	v_mul_f32_e32 v37, v30, v31
	v_add_f32_e32 v47, v47, v97
	v_pk_mul_f32 v[30:31], v[150:151], v[60:61]
	v_rcp_f32_e32 v150, v164
	v_add_f32_e32 v105, v78, v79
	v_mul_f32_e32 v55, v46, v47
	v_pk_mul_f32 v[46:47], v[152:153], v[68:69]
	v_rcp_f32_e32 v152, v181
	v_pk_mul_f32 v[78:79], v[94:95], v[138:139]
	v_add_f32_e32 v31, v31, v105
	v_pk_mul_f32 v[24:25], v[88:89], v[24:25]
	v_rcp_f32_e32 v88, v160
	v_and_b32_e32 v117, 0xffff0000, v125
	v_add_f32_e32 v165, 1.0, v165
	v_add_f32_e32 v172, v80, v81
	v_pk_mul_f32 v[80:81], v[154:155], v[100:101]
	v_add_f32_e32 v75, v78, v79
	v_mul_f32_e32 v60, v30, v31
	v_add_f32_e32 v25, v25, v168
	v_pk_mul_f32 v[30:31], v[148:149], v[38:39]
	v_rcp_f32_e32 v148, v196
	v_add_f32_e32 v99, v80, v81
	v_pk_mul_f32 v[80:81], v[92:93], v[116:117]
	v_add_f32_e32 v47, v47, v75
	v_mul_f32_e32 v38, v24, v25
	v_add_f32_e32 v31, v31, v98
	v_pk_mul_f32 v[24:25], v[150:151], v[56:57]
	v_rcp_f32_e32 v150, v165
	v_pk_mul_f32 v[90:91], v[154:155], v[106:107]
	v_add_f32_e32 v106, v80, v81
	v_pk_mul_f32 v[80:81], v[94:95], v[130:131]
	v_mul_f32_e32 v46, v46, v47
	v_mul_f32_e32 v47, v30, v31
	v_pk_mul_f32 v[30:31], v[152:153], v[62:63]
	v_rcp_f32_e32 v152, v182
	v_add_f32_e32 v76, v80, v81
	v_add_f32_e32 v25, v25, v106
	v_pk_mul_f32 v[20:21], v[88:89], v[20:21]
	v_rcp_f32_e32 v88, v161
	v_add_f32_e32 v176, 1.0, v176
	v_mul_f32_e32 v56, v24, v25
	v_add_f32_e32 v31, v31, v76
	v_add_f32_e32 v21, v21, v169
	v_pk_mul_f32 v[24:25], v[148:149], v[32:33]
	v_rcp_f32_e32 v148, v197
	v_add_f32_e32 v100, v84, v85
	v_pk_mul_f32 v[84:85], v[92:93], v[118:119]
	v_mul_f32_e32 v30, v30, v31
	v_mul_f32_e32 v31, v20, v21
	v_add_f32_e32 v25, v25, v99
	v_pk_mul_f32 v[20:21], v[150:151], v[48:49]
	v_rcp_f32_e32 v150, v176
	v_add_f32_e32 v107, v84, v85
	v_pk_mul_f32 v[84:85], v[94:95], v[136:137]
	v_mul_f32_e32 v32, v24, v25
	v_pk_mul_f32 v[24:25], v[152:153], v[58:59]
	v_rcp_f32_e32 v152, v183
	v_add_f32_e32 v77, v84, v85
	v_add_f32_e32 v21, v21, v107
	v_pk_mul_f32 v[18:19], v[88:89], v[18:19]
	v_rcp_f32_e32 v88, v170
	v_add_f32_e32 v177, 1.0, v177
	v_mul_f32_e32 v33, v20, v21
	v_add_f32_e32 v25, v25, v77
	v_add_f32_e32 v19, v19, v172
	v_pk_mul_f32 v[20:21], v[148:149], v[28:29]
	v_rcp_f32_e32 v148, v198
	v_add_f32_e32 v101, v86, v87
	v_pk_mul_f32 v[86:87], v[92:93], v[120:121]
	v_mul_f32_e32 v24, v24, v25
	v_mul_f32_e32 v25, v18, v19
	v_add_f32_e32 v21, v21, v100
	v_pk_mul_f32 v[18:19], v[150:151], v[42:43]
	v_rcp_f32_e32 v150, v177
	v_add_f32_e32 v171, 1.0, v171
	v_add_f32_e32 v108, v86, v87
	v_pk_mul_f32 v[86:87], v[94:95], v[132:133]
	v_cvt_pk_bf16_f32 v37, v37, v38
	v_cvt_pk_bf16_f32 v38, v31, v25
	v_mul_f32_e32 v25, v20, v21
	v_pk_mul_f32 v[20:21], v[152:153], v[52:53]
	v_rcp_f32_e32 v152, v184
	v_add_f32_e32 v78, v86, v87
	v_add_f32_e32 v19, v19, v108
	v_pk_mul_f32 v[16:17], v[88:89], v[16:17]
	v_rcp_f32_e32 v88, v171
	v_lshlrev_b32_e32 v125, 16, v127
	v_add_f32_e32 v178, 1.0, v178
	v_mul_f32_e32 v28, v18, v19
	v_add_f32_e32 v21, v21, v78
	v_add_f32_e32 v17, v17, v173
	v_pk_mul_f32 v[18:19], v[148:149], v[26:27]
	v_rcp_f32_e32 v148, v199
	v_add_f32_e32 v102, v90, v91
	v_pk_mul_f32 v[90:91], v[92:93], v[124:125]
	v_mul_f32_e32 v26, v20, v21
	v_mul_f32_e32 v20, v16, v17
	v_add_f32_e32 v19, v19, v101
	v_pk_mul_f32 v[16:17], v[150:151], v[40:41]
	v_rcp_f32_e32 v150, v178
	v_add_f32_e32 v109, v90, v91
	v_pk_mul_f32 v[90:91], v[94:95], v[134:135]
	v_mul_f32_e32 v27, v18, v19
	v_pk_mul_f32 v[18:19], v[152:153], v[50:51]
	v_rcp_f32_e32 v152, v185
	v_and_b32_e32 v127, 0xffff0000, v127
	v_add_f32_e32 v79, v90, v91
	v_add_f32_e32 v17, v17, v109
	v_pk_mul_f32 v[12:13], v[88:89], v[12:13]
	v_pk_mul_f32 v[92:93], v[92:93], v[126:127]
	v_mul_f32_e32 v29, v16, v17
	v_add_f32_e32 v19, v19, v79
	v_add_f32_e32 v13, v13, v186
	v_pk_mul_f32 v[16:17], v[148:149], v[22:23]
	v_add_f32_e32 v110, v92, v93
	v_pk_mul_f32 v[92:93], v[94:95], v[142:143]
	v_mul_f32_e32 v22, v18, v19
	v_mul_f32_e32 v18, v12, v13
	v_add_f32_e32 v17, v17, v102
	v_pk_mul_f32 v[12:13], v[150:151], v[34:35]
	v_add_f32_e32 v80, v92, v93
	v_cvt_pk_bf16_f32 v39, v20, v18
	v_mul_f32_e32 v19, v16, v17
	v_add_f32_e32 v13, v13, v110
	v_pk_mul_f32 v[20:21], v[152:153], v[44:45]
	v_mul_f32_e32 v71, v72, v71
	v_add_f32_e32 v67, v67, v73
	s_cmp_eq_u64 s[54:55], exec
	s_cbranch_scc1 .Lp3wt_0
	global_store_dwordx4 v5, v[36:39], s[18:19]
	s_branch .Lp3wt_0_e
.Lp3wt_0:
	global_store_dwordx4 v5, v[36:39], s[18:19] sc0 sc1
.Lp3wt_0_e:
	v_cvt_pk_bf16_f32 v16, v70, v1
	v_cvt_pk_bf16_f32 v17, v55, v47
	v_cvt_pk_bf16_f32 v18, v32, v25
	v_cvt_pk_bf16_f32 v19, v27, v19
	v_mul_f32_e32 v1, v12, v13
	v_add_f32_e32 v5, v21, v80
	s_cmp_eq_u64 s[54:55], exec
	s_cbranch_scc1 .Lp3wt_1
	global_store_dwordx4 v[10:11], v[16:19], off
	s_branch .Lp3wt_1_e
.Lp3wt_1:
	global_store_dwordx4 v[10:11], v[16:19], off sc0 sc1
.Lp3wt_1_e:
	v_cvt_pk_bf16_f32 v10, v71, v64
	v_cvt_pk_bf16_f32 v11, v60, v56
	v_mul_f32_e32 v66, v66, v67
	v_cvt_pk_bf16_f32 v12, v33, v28
	v_cvt_pk_bf16_f32 v13, v29, v1
	v_mul_f32_e32 v1, v20, v5
	s_cmp_eq_u64 s[54:55], exec
	s_cbranch_scc1 .Lp3wt_2
	global_store_dwordx4 v[8:9], v[10:13], off
	s_branch .Lp3wt_2_e
.Lp3wt_2:
	global_store_dwordx4 v[8:9], v[10:13], off sc0 sc1
.Lp3wt_2_e:
	v_cvt_pk_bf16_f32 v8, v66, v54
	v_cvt_pk_bf16_f32 v9, v46, v30
	s_nop 1
	v_cvt_pk_bf16_f32 v10, v24, v26
	v_cvt_pk_bf16_f32 v11, v22, v1
	s_cmp_eq_u64 s[54:55], exec
	s_cbranch_scc1 .Lp3wt_3
	global_store_dwordx4 v[6:7], v[8:11], off
	s_branch .Lp3wt_3_e
.Lp3wt_3:
	global_store_dwordx4 v[6:7], v[8:11], off sc0 sc1
.Lp3wt_3_e:
	s_andn2_b64 exec, exec, s[54:55]
	s_cbranch_execnz .LBB0_437
